# attention: the two xor-32 lane exchanges per key tile (row max, row sum) use v_permlane32_swap instead of ds_bpermute + lgkm wait (instruction selection: no LDS round trip); same values
# speedup vs baseline: 1.0046x; 1.0038x over previous
.Lmy_kpf_b:
	s_nop 11
	v_mov_b32_e32 v96, v42
	v_mov_b32_e32 v116, v43
	v_mov_b32_e32 v42, v34
	v_mov_b32_e32 v43, v36
	v_pk_fma_f32 v[42:43], v[42:43], s[16:17], v[156:157] op_sel_hi:[1,0,1] neg_lo:[0,0,1] neg_hi:[0,0,1]
	v_mov_b32_e32 v36, v35
	v_cndmask_b32_e32 v0, v126, v43, vcc
	v_cmp_gt_u32_e32 vcc, s21, v176
	v_mov_b32_e32 v110, v46
	v_pk_fma_f32 v[36:37], v[36:37], s[16:17], v[158:159] op_sel_hi:[1,0,1] neg_lo:[0,0,1] neg_hi:[0,0,1]
	v_cndmask_b32_e32 v46, v126, v42, vcc
	v_cmp_gt_u32_e32 vcc, s21, v177
	v_mov_b32_e32 v108, v47
	v_mov_b32_e32 v34, v38
	v_mov_b32_e32 v35, v40
	v_mov_b32_e32 v40, v39
	v_pk_mul_f32 v[38:39], v[96:97], v[90:91]
	v_cvt_f32_i32_e32 v91, v163
	v_cndmask_b32_e32 v47, v126, v37, vcc
	v_cmp_gt_u32_e32 vcc, s21, v178
	v_mov_b32_e32 v106, v48
	v_pk_fma_f32 v[34:35], v[34:35], s[16:17], v[160:161] op_sel_hi:[1,0,1] neg_lo:[0,0,1] neg_hi:[0,0,1]
	v_cndmask_b32_e32 v48, v126, v36, vcc
	v_cmp_gt_u32_e32 vcc, s21, v179
	v_mov_b32_e32 v104, v49
	v_mov_b32_e32 v154, v44
	v_cndmask_b32_e32 v49, v126, v35, vcc
	v_cmp_gt_u32_e32 vcc, s21, v180
	v_mov_b32_e32 v112, v45
	v_mov_b32_e32 v44, v38
	v_cndmask_b32_e32 v96, v126, v34, vcc
	v_max3_f32 v34, v46, s22, v48
	v_max3_f32 v114, v34, v0, v47
	v_pk_mul_f32 v[34:35], v[154:155], v[90:91]
	v_cvt_f32_i32_e32 v91, v170
	v_mov_b32_e32 v45, v34
	v_mov_b32_e32 v34, v39
	v_pk_add_f32 v[34:35], v[44:45], v[34:35] neg_lo:[0,1] neg_hi:[0,1]
	v_pk_mul_f32 v[36:37], v[116:117], v[90:91]
	v_cvt_f32_i32_e32 v91, v169
	v_cmp_gt_u32_e32 vcc, s21, v163
	v_mov_b32_e32 v38, v36
	s_nop 0
	v_cndmask_b32_e32 v44, v126, v35, vcc
	v_cmp_gt_u32_e32 vcc, s21, v168
	s_nop 1
	v_cndmask_b32_e32 v45, v126, v34, vcc
	v_pk_mul_f32 v[34:35], v[112:113], v[90:91]
	v_cvt_f32_i32_e32 v91, v172
	v_mov_b32_e32 v39, v34
	v_mov_b32_e32 v34, v37
	v_pk_add_f32 v[34:35], v[38:39], v[34:35] neg_lo:[0,1] neg_hi:[0,1]
	v_pk_mul_f32 v[36:37], v[110:111], v[90:91]
	v_cvt_f32_i32_e32 v91, v174
	v_cmp_gt_u32_e32 vcc, s21, v169
	v_pk_mul_f32 v[38:39], v[108:109], v[90:91]
	v_cvt_f32_i32_e32 v91, v171
	v_cndmask_b32_e32 v110, v126, v35, vcc
	v_cmp_gt_u32_e32 vcc, s21, v170
	v_pk_mul_f32 v[42:43], v[106:107], v[90:91]
	v_cvt_f32_i32_e32 v91, v173
	v_cndmask_b32_e32 v108, v126, v34, vcc
	v_mov_b32_e32 v34, v36
	v_mov_b32_e32 v35, v42
	v_mov_b32_e32 v42, v37
	v_pk_add_f32 v[34:35], v[34:35], v[42:43] neg_lo:[0,1] neg_hi:[0,1]
	v_cmp_gt_u32_e32 vcc, s21, v171
	v_mov_b32_e32 v36, v38
	s_nop 0
	v_cndmask_b32_e32 v42, v126, v35, vcc
	v_cmp_gt_u32_e32 vcc, s21, v172
	s_nop 1
	v_cndmask_b32_e32 v43, v126, v34, vcc
	v_pk_mul_f32 v[34:35], v[104:105], v[90:91]
	v_cmp_gt_u32_e32 vcc, s21, v173
	v_mov_b32_e32 v37, v34
	v_mov_b32_e32 v34, v39
	v_pk_add_f32 v[34:35], v[36:37], v[34:35] neg_lo:[0,1] neg_hi:[0,1]
	s_nop 0
	v_cndmask_b32_e32 v91, v126, v35, vcc
	v_cmp_gt_u32_e32 vcc, s21, v174
	s_nop 1
	v_cndmask_b32_e32 v104, v126, v34, vcc
	v_pk_mul_f32 v[34:35], v[102:103], v[164:165]
	v_cmp_gt_u32_e32 vcc, s21, v182
	v_pk_fma_f32 v[34:35], v[40:41], s[16:17], v[34:35] op_sel_hi:[1,0,1] neg_lo:[0,0,1] neg_hi:[0,0,1]
	s_nop 0
	v_cndmask_b32_e32 v105, v126, v35, vcc
	v_cmp_gt_u32_e32 vcc, s21, v183
	s_nop 1
	v_cndmask_b32_e32 v106, v126, v34, vcc
	v_max3_f32 v34, v114, v96, v106
	v_max3_f32 v34, v34, v49, v105
	v_max3_f32 v34, v34, v45, v108
	v_max3_f32 v34, v34, v44, v110
	v_max3_f32 v34, v34, v43, v104
	v_max3_f32 v34, v34, v42, v91
	v_mov_b32_e32 v35, v34
	s_nop 1
	v_permlane32_swap_b32_e32 v35, v34
	v_max3_f32 v107, v133, v34, v35
	v_sub_f32_e32 v34, v46, v107
	v_sub_f32_e32 v111, v133, v107
	v_mov_b32_e32 v133, v107
	v_exp_f32_e32 v109, v34
	ds_read_b64_tr_b16 v[38:39], v124
	ds_read_b64_tr_b16 v[40:41], v124 offset:1024
	ds_read_b64_tr_b16 v[36:37], v124 offset:1088
	ds_read_b64_tr_b16 v[34:35], v124 offset:64
	v_sub_f32_e32 v112, v48, v107
	s_nop 1
	v_sub_f32_e32 v113, v0, v107
	v_exp_f32_e32 v112, v112
	s_nop 0
	v_exp_f32_e32 v113, v113
	v_cmp_lt_f32_e32 vcc, s23, v0
	v_sub_f32_e32 v0, v47, v107
	v_cmp_lt_f32_e64 s[2:3], s23, v46
	v_cndmask_b32_e32 v113, 0, v113, vcc
	s_nop 0
	v_cndmask_b32_e64 v46, 0, v109, s[2:3]
	s_nop 0
	v_exp_f32_e32 v0, v0
	v_cmp_lt_f32_e32 vcc, s23, v47
	s_nop 0
	s_nop 0
	v_cndmask_b32_e32 v47, 0, v0, vcc
	v_cmp_lt_f32_e32 vcc, s23, v48
	v_sub_f32_e32 v0, v96, v107
	s_nop 0
	v_cndmask_b32_e32 v48, 0, v112, vcc
	s_nop 1
	v_sub_f32_e32 v109, v49, v107
	v_exp_f32_e32 v0, v0
	s_nop 0
	v_exp_f32_e32 v109, v109
	v_cmp_lt_f32_e32 vcc, s23, v49
	s_nop 1
	v_cndmask_b32_e32 v49, 0, v109, vcc
	v_cmp_lt_f32_e32 vcc, s23, v96
	s_nop 1
	v_cndmask_b32_e32 v96, 0, v0, vcc
	v_sub_f32_e32 v0, v106, v107
	s_nop 1
	v_sub_f32_e32 v109, v105, v107
	v_exp_f32_e32 v0, v0
	s_nop 0
	v_exp_f32_e32 v109, v109
	v_cmp_lt_f32_e32 vcc, s23, v105
	s_nop 1
	v_cndmask_b32_e32 v105, 0, v109, vcc
	v_cmp_lt_f32_e32 vcc, s23, v106
	s_nop 1
	v_cndmask_b32_e32 v106, 0, v0, vcc
	v_sub_f32_e32 v0, v45, v107
	s_nop 1
	v_sub_f32_e32 v109, v44, v107
	v_exp_f32_e32 v0, v0
	s_nop 0
	v_exp_f32_e32 v109, v109
	v_cmp_lt_f32_e32 vcc, s23, v44
	s_nop 1
	v_cndmask_b32_e32 v109, 0, v109, vcc
	v_cmp_lt_f32_e32 vcc, s23, v45
	s_nop 1
	v_cndmask_b32_e32 v112, 0, v0, vcc
	v_sub_f32_e32 v0, v108, v107
	s_nop 1
	v_sub_f32_e32 v44, v110, v107
	v_exp_f32_e32 v0, v0
	s_nop 0
	v_exp_f32_e32 v44, v44
	v_cmp_lt_f32_e32 vcc, s23, v110
	s_nop 1
	v_cndmask_b32_e32 v110, 0, v44, vcc
	v_cmp_lt_f32_e32 vcc, s23, v108
	s_nop 1
	v_cndmask_b32_e32 v108, 0, v0, vcc
	v_sub_f32_e32 v0, v43, v107
	s_nop 1
	v_sub_f32_e32 v44, v42, v107
	v_exp_f32_e32 v0, v0
	s_nop 0
	v_exp_f32_e32 v44, v44
	v_cmp_lt_f32_e32 vcc, s23, v42
	v_bfe_u32 v45, v48, 16, 1
	s_nop 0
	v_cndmask_b32_e32 v114, 0, v44, vcc
	v_cmp_lt_f32_e32 vcc, s23, v43
	v_bfe_u32 v44, v47, 16, 1
	s_nop 0
	v_cndmask_b32_e32 v115, 0, v0, vcc
	v_sub_f32_e32 v0, v104, v107
	s_nop 1
	v_sub_f32_e32 v42, v91, v107
	v_exp_f32_e32 v0, v0
	s_nop 0
	v_exp_f32_e32 v42, v42
	v_cmp_lt_f32_e32 vcc, s23, v91
	v_bfe_u32 v43, v106, 16, 1
	v_add3_u32 v43, v106, v43, s28
	v_cndmask_b32_e32 v91, 0, v42, vcc
	v_cmp_lt_f32_e32 vcc, s23, v104
	s_nop 1
	v_cndmask_b32_e32 v104, 0, v0, vcc
	v_add_f32_e32 v0, v46, v48
	v_add_f32_e32 v0, v113, v0
	v_add_f32_e32 v0, v47, v0
	v_add_f32_e32 v0, v96, v0
	v_add_f32_e32 v0, v106, v0
	v_add_f32_e32 v0, v49, v0
	v_add_f32_e32 v0, v105, v0
	v_add_f32_e32 v0, v112, v0
	v_add_f32_e32 v0, v108, v0
	v_add_f32_e32 v0, v109, v0
	v_mov_b32_e32 v42, v111
	v_add_f32_e32 v0, v110, v0
	v_exp_f32_e32 v42, v42
	v_add_f32_e32 v0, v115, v0
	v_add_f32_e32 v0, v104, v0
	v_add_f32_e32 v111, v114, v0
	v_mov_b32_e32 v0, v42
	v_bfe_u32 v42, v105, 16, 1
	v_add3_u32 v48, v48, v45, s28
	v_add3_u32 v47, v47, v44, s28
	v_add3_u32 v42, v105, v42, s28
	v_bfe_u32 v44, v46, 16, 1
	v_bfe_u32 v45, v113, 16, 1
	v_bfe_u32 v105, v96, 16, 1
	v_bfe_u32 v106, v49, 16, 1
	v_add3_u32 v49, v49, v106, s28
	v_add3_u32 v96, v96, v105, s28
	v_add3_u32 v45, v113, v45, s28
	v_add3_u32 v44, v46, v44, s28
	v_lshrrev_b32_e32 v46, 16, v44
	v_lshrrev_b32_e32 v105, 16, v45
	v_lshrrev_b32_e32 v44, 16, v96
	v_lshrrev_b32_e32 v45, 16, v49
	v_pk_mul_f32 v[32:33], v[32:33], v[0:1] op_sel_hi:[1,0]
	v_pk_mul_f32 v[30:31], v[30:31], v[0:1] op_sel_hi:[1,0]
	v_pk_mul_f32 v[28:29], v[28:29], v[0:1] op_sel_hi:[1,0]
	v_pk_mul_f32 v[26:27], v[26:27], v[0:1] op_sel_hi:[1,0]
	v_pk_mul_f32 v[24:25], v[24:25], v[0:1] op_sel_hi:[1,0]
	v_pk_mul_f32 v[22:23], v[22:23], v[0:1] op_sel_hi:[1,0]
	v_pk_mul_f32 v[20:21], v[20:21], v[0:1] op_sel_hi:[1,0]
	v_pk_mul_f32 v[18:19], v[18:19], v[0:1] op_sel_hi:[1,0]
	v_pk_mul_f32 v[16:17], v[16:17], v[0:1] op_sel_hi:[1,0]
	v_and_or_b32 v45, v42, s29, v45
	v_and_or_b32 v44, v43, s29, v44
	v_and_or_b32 v43, v47, s29, v105
	v_and_or_b32 v42, v48, s29, v46
	v_pk_mul_f32 v[14:15], v[14:15], v[0:1] op_sel_hi:[1,0]
	v_pk_mul_f32 v[12:13], v[12:13], v[0:1] op_sel_hi:[1,0]
	v_pk_mul_f32 v[10:11], v[10:11], v[0:1] op_sel_hi:[1,0]
	v_pk_mul_f32 v[8:9], v[8:9], v[0:1] op_sel_hi:[1,0]
	v_pk_mul_f32 v[6:7], v[6:7], v[0:1] op_sel_hi:[1,0]
	v_pk_mul_f32 v[4:5], v[4:5], v[0:1] op_sel_hi:[1,0]
	v_pk_mul_f32 v[2:3], v[2:3], v[0:1] op_sel_hi:[1,0]
	s_waitcnt lgkmcnt(2)
	v_mfma_f32_32x32x16_bf16 v[18:33], v[38:41], v[42:45], v[18:33]
	s_waitcnt lgkmcnt(0)
	v_mfma_f32_32x32x16_bf16 v[2:17], v[34:37], v[42:45], v[2:17]
	v_bfe_u32 v34, v91, 16, 1
	v_bfe_u32 v35, v104, 16, 1
	v_bfe_u32 v36, v110, 16, 1
	v_bfe_u32 v37, v108, 16, 1
	v_add3_u32 v38, v108, v37, s28
	v_add3_u32 v39, v110, v36, s28
	v_add3_u32 v40, v104, v35, s28
	v_add3_u32 v41, v91, v34, s28
	v_bfe_u32 v34, v112, 16, 1
	v_bfe_u32 v35, v109, 16, 1
	v_bfe_u32 v36, v115, 16, 1
	v_bfe_u32 v37, v114, 16, 1
	v_add3_u32 v42, v114, v37, s28
	v_add3_u32 v43, v115, v36, s28
	v_add3_u32 v35, v109, v35, s28
	v_add3_u32 v34, v112, v34, s28
	v_lshrrev_b32_e32 v44, 16, v34
	v_lshrrev_b32_e32 v45, 16, v35
	ds_read_b64_tr_b16 v[34:35], v124 offset:2048
	ds_read_b64_tr_b16 v[36:37], v124 offset:3072
	v_lshrrev_b32_e32 v43, 16, v43
	v_lshrrev_b32_e32 v42, 16, v42
	v_and_or_b32 v41, v41, s29, v42
	v_and_or_b32 v40, v40, s29, v43
	v_and_or_b32 v39, v39, s29, v45
	v_and_or_b32 v38, v38, s29, v44
	ds_read_b64_tr_b16 v[44:45], v124 offset:3136
	ds_read_b64_tr_b16 v[42:43], v124 offset:2112
	s_waitcnt lgkmcnt(2)
	v_mfma_f32_32x32x16_bf16 v[18:33], v[34:37], v[38:41], v[18:33]
	v_add_f32_e32 v34, v91, v111
	v_mov_b32_e32 v35, v34
	s_nop 1
	v_permlane32_swap_b32_e32 v35, v34
	s_waitcnt lgkmcnt(0)
	s_waitcnt lgkmcnt(0)
	v_add_f32_e32 v34, v34, v35
	v_mfma_f32_32x32x16_bf16 v[2:17], v[42:45], v[38:41], v[2:17]
	v_fmac_f32_e32 v34, v130, v0
	v_mov_b32_e32 v130, v34
	s_branch .LBB0_626
